# v12: first seam uses the XCD barrier instead of cg grid sync; census counter loads batched
# speedup vs baseline: 1.0033x; 1.0033x over previous
.LBB0_524:
	v_readlane_b32 s1, v243, 57
	s_add_i32 s22, s1, 1
	v_readlane_b32 s2, v242, 0
	s_cmp_le_i32 s2, s22
	v_readlane_b32 s23, v243, 60
	s_cbranch_scc1 .LBB0_9
	v_readlane_b32 s4, v243, 53
	s_cmp_lg_u32 s1, s4
	s_mov_b64 s[2:3], -1
	v_readlane_b32 s5, v243, 54
	v_readlane_b32 s6, v243, 55
	v_readlane_b32 s7, v243, 56
	s_getreg_b32 s1, hwreg(HW_REG_XCC_ID, 0, 4)
	s_waitcnt vmcnt(0)
	s_waitcnt vmcnt(0)
	s_barrier
	s_mov_b64 s[2:3], exec
	v_readlane_b32 s4, v243, 6
	v_readlane_b32 s5, v243, 7
	s_and_b64 s[4:5], s[2:3], s[4:5]
	s_mov_b64 exec, s[4:5]
	s_cbranch_execz .LBB0_578
	v_readlane_b32 s4, v243, 51
	s_waitcnt vmcnt(0) expcnt(0) lgkmcnt(0)
	s_and_b32 s10, s1, 15
	v_mov_b32_e32 v0, s4
	ds_read_b32 v2, v0
	v_readlane_b32 s4, v243, 52
	s_waitcnt lgkmcnt(0)
	v_cmp_ne_u32_e32 vcc, 0, v2
	v_mov_b32_e32 v0, s4
	ds_read_b32 v0, v0
	s_cbranch_vccnz .LBB0_542
	s_mov_b32 s1, 1
	s_branch .LBB0_530

.LBB0_530:
	v_readlane_b32 s4, v243, 13
	v_readlane_b32 s5, v243, 14
	v_readlane_b32 s6, v243, 10
	s_waitcnt lgkmcnt(0)
	s_nop 2
	global_load_dword v0, v101, s[4:5] sc1
	v_readlane_b32 s4, v243, 15
	v_readlane_b32 s5, v243, 16
	s_nop 4
	global_load_dword v1, v101, s[4:5] sc1
	v_readlane_b32 s4, v243, 17
	v_readlane_b32 s5, v243, 18
	s_nop 2
	s_nop 1
	global_load_dword v2, v101, s[4:5] sc1
	v_readlane_b32 s4, v243, 19
	v_readlane_b32 s5, v243, 20
	s_nop 2
	s_nop 1
	global_load_dword v3, v101, s[4:5] sc1
	v_readlane_b32 s4, v243, 21
	v_readlane_b32 s5, v243, 22
	s_nop 2
	s_nop 1
	global_load_dword v4, v101, s[4:5] sc1
	v_readlane_b32 s4, v243, 23
	v_readlane_b32 s5, v243, 24
	s_nop 2
	s_nop 1
	global_load_dword v5, v101, s[4:5] sc1
	v_readlane_b32 s4, v243, 25
	v_readlane_b32 s5, v243, 26
	s_nop 2
	s_nop 1
	global_load_dword v6, v101, s[4:5] sc1
	v_readlane_b32 s4, v243, 27
	v_readlane_b32 s5, v243, 28
	s_nop 2
	s_nop 1
	global_load_dword v7, v101, s[4:5] sc1
	v_readlane_b32 s4, v243, 29
	v_readlane_b32 s5, v243, 30
	s_nop 2
	s_nop 1
	global_load_dword v8, v101, s[4:5] sc1
	v_readlane_b32 s4, v243, 31
	v_readlane_b32 s5, v243, 32
	s_nop 2
	s_nop 1
	global_load_dword v9, v101, s[4:5] sc1
	v_readlane_b32 s4, v243, 33
	v_readlane_b32 s5, v243, 34
	s_nop 2
	s_nop 1
	global_load_dword v10, v101, s[4:5] sc1
	v_readlane_b32 s4, v243, 35
	v_readlane_b32 s5, v243, 36
	s_nop 2
	s_nop 1
	global_load_dword v11, v101, s[4:5] sc1
	v_readlane_b32 s4, v243, 37
	v_readlane_b32 s5, v243, 38
	s_nop 2
	s_nop 1
	global_load_dword v12, v101, s[4:5] sc1
	v_readlane_b32 s4, v243, 39
	v_readlane_b32 s5, v243, 40
	s_nop 2
	s_nop 1
	global_load_dword v13, v101, s[4:5] sc1
	v_readlane_b32 s4, v243, 41
	v_readlane_b32 s5, v243, 42
	s_nop 2
	s_nop 1
	global_load_dword v14, v101, s[4:5] sc1
	v_readlane_b32 s4, v243, 43
	v_readlane_b32 s5, v243, 44
	s_nop 2
	s_nop 1
	global_load_dword v15, v101, s[4:5] sc1
	s_mov_b64 s[4:5], -1
	s_waitcnt vmcnt(0)
	v_add_u32_e32 v16, v1, v0
	v_add_u32_e32 v16, v16, v2
	v_add_u32_e32 v16, v16, v3
	v_add_u32_e32 v16, v16, v4
	v_add_u32_e32 v16, v16, v5
	v_add_u32_e32 v16, v16, v6
	v_add_u32_e32 v16, v16, v7
	v_add_u32_e32 v16, v16, v8
	v_add_u32_e32 v16, v16, v9
	v_add_u32_e32 v16, v16, v10
	v_add_u32_e32 v16, v16, v11
	v_add_u32_e32 v16, v16, v12
	v_add_u32_e32 v16, v16, v13
	v_add_u32_e32 v16, v16, v14
	v_add_u32_e32 v16, v16, v15
	v_cmp_eq_u32_e32 vcc, s6, v16
	s_mov_b64 s[6:7], -1
	s_cbranch_vccnz .LBB0_529
	s_and_b32 s4, s1, 0xff
	s_cmp_eq_u32 s4, 0
	s_mov_b64 s[4:5], -1
	s_mov_b64 s[8:9], -1
	s_sleep 1
	s_cbranch_scc1 .LBB0_534
	s_and_b64 vcc, exec, s[8:9]
	s_cbranch_vccz .LBB0_529
